# LayerNorm row loads marked non-temporal (rows are streamed once)
# speedup vs baseline: 1.0131x; 1.0046x over previous
; DEV void ln_rows(float* hbuf, bf16* hb, const float* g, const float* bta, float* stats, bool write_h, int gw, int NGW, int lane) {
;     ...
;     for (int m0 = gw; m0 < NTOK; m0 += 2 * NGW) {
;         f32x4 v[2][4]; float s[2];
; #pragma unroll
;         for (int q = 0; q < 2; ++q) { const f32x4* xr = (const f32x4*)(hbuf + (size_t)(m0 + q * NGW) * DM) + lane;
; #pragma unroll
;             for (int j = 0; j < 4; ++j) v[q][j] = xr[64 * j]; }
; #pragma unroll
;         for (int q = 0; q < 2; ++q) { float t = 0.f;
; #pragma unroll
;             for (int j = 0; j < 4; ++j) t += (v[q][j].x + v[q][j].y) + (v[q][j].z + v[q][j].w);
;             s[q] = t; }
; #pragma unroll
;         for (int q = 0; q < 2; ++q) {
;             const int m = m0 + q * NGW;
;             const float mean = wave_sum(s[q], lane) * (1.f / DM); float s2 = 0.f;
; #pragma unroll
;             for (int j = 0; j < 4; ++j) { v[q][j] = v[q][j] - mean; s2 += (v[q][j].x * v[q][j].x + v[q][j].y * v[q][j].y) + (v[q][j].z * v[q][j].z + v[q][j].w * v[q][j].w); }
;             const float rstd = 1.f / sqrtf(wave_sum(s2, lane) * (1.f / DM) + 1e-5f);
;             if (lane == 0) { f32x2_ st2; st2.x = mean; st2.y = rstd; *(f32x2_*)(stats + 2 * m) = st2; }
.LBB0_321:
	s_ashr_i32 s27, s26, 31
	s_lshl_b64 s[6:7], s[26:27], 12
	v_lshl_add_u64 v[0:1], v[32:33], 0, s[6:7]
	global_load_dwordx4 v[28:31], v[0:1], off nt
	global_load_dwordx4 v[24:27], v[0:1], off offset:1024 nt
	global_load_dwordx4 v[20:23], v[0:1], off offset:2048 nt
	global_load_dwordx4 v[12:15], v[0:1], off offset:3072 nt
	s_add_i32 s24, s26, s44
	s_ashr_i32 s25, s24, 31
	s_lshl_b64 s[6:7], s[24:25], 12
	s_waitcnt vmcnt(3)
	v_mov_b32_e32 v0, v29
	v_mov_b32_e32 v1, v30
	v_mov_b32_e32 v2, v28
	v_mov_b32_e32 v3, v31
	s_waitcnt vmcnt(2)
	v_mov_b32_e32 v4, v25
	v_mov_b32_e32 v5, v26
	v_mov_b32_e32 v6, v24
	v_mov_b32_e32 v7, v27
	v_pk_add_f32 v[0:1], v[0:1], v[2:3]
	v_pk_add_f32 v[2:3], v[4:5], v[6:7]
	v_add_f32_e32 v6, v0, v1
	v_pk_add_f32 v[0:1], v[2:3], v[2:3] op_sel:[0,1] op_sel_hi:[1,0]
	s_waitcnt vmcnt(1)
	v_add_f32_e32 v8, v20, v21
	v_add_f32_e32 v10, v22, v23
	s_waitcnt vmcnt(0)
	v_mov_b32_e32 v17, v12
	v_mov_b32_e32 v9, v14
	v_mov_b32_e32 v11, v15
	v_add_f32_e32 v16, 0, v6
	v_mov_b32_e32 v1, v13
	v_pk_add_f32 v[4:5], v[8:9], v[10:11]
	v_pk_add_f32 v[0:1], v[16:17], v[0:1]
	s_nop 0
	v_pk_add_f32 v[0:1], v[0:1], v[4:5]
	s_nop 0
	v_add_f32_e32 v0, v0, v1
	s_nop 1
	v_add_f32_dpp v0, v0, v0 quad_perm:[1,0,3,2] row_mask:0xf bank_mask:0xf bound_ctrl:1
	s_nop 1
	v_add_f32_dpp v0, v0, v0 quad_perm:[2,3,0,1] row_mask:0xf bank_mask:0xf bound_ctrl:1
	s_nop 1
	v_add_f32_dpp v0, v0, v0 row_half_mirror row_mask:0xf bank_mask:0xf bound_ctrl:1
	s_nop 1
	v_add_f32_dpp v2, v0, v0 row_mirror row_mask:0xf bank_mask:0xf bound_ctrl:1
	ds_bpermute_b32 v3, v42, v2
	v_lshl_add_u64 v[0:1], v[32:33], 0, s[6:7]
	s_waitcnt lgkmcnt(0)
	v_add_f32_e32 v40, v2, v3
	global_load_dwordx4 v[16:19], v[0:1], off nt
	global_load_dwordx4 v[8:11], v[0:1], off offset:1024 nt
	global_load_dwordx4 v[4:7], v[0:1], off offset:2048 nt
	s_nop 0
	global_load_dwordx4 v[0:3], v[0:1], off offset:3072 nt
	ds_bpermute_b32 v41, v43, v40
	s_waitcnt lgkmcnt(0)
	v_add_f32_e32 v47, v40, v41
	v_fmamk_f32 v41, v47, 0xba800000, v31
	v_fmamk_f32 v29, v47, 0xba800000, v29
	v_fmamk_f32 v31, v47, 0xba800000, v27
	v_fmamk_f32 v25, v47, 0xba800000, v25
	v_fmamk_f32 v40, v47, 0xba800000, v30
	v_fmac_f32_e32 v28, 0xba800000, v47
	v_fmamk_f32 v30, v47, 0xba800000, v26
	v_fmac_f32_e32 v24, 0xba800000, v47
	v_fmamk_f32 v27, v47, 0xba800000, v23
	v_fmamk_f32 v26, v47, 0xba800000, v22
	v_fmamk_f32 v21, v47, 0xba800000, v21
	v_mul_f32_e32 v22, v29, v29
	v_mul_f32_e32 v23, v41, v41
	v_mul_f32_e32 v48, v25, v25
	v_mul_f32_e32 v49, v31, v31
	v_fmac_f32_e32 v20, 0xba800000, v47
	v_fmamk_f32 v15, v47, 0xba800000, v15
	v_fmamk_f32 v13, v47, 0xba800000, v13
	v_mul_f32_e32 v50, v21, v21
	v_mul_f32_e32 v51, v27, v27
	v_fmac_f32_e32 v22, v28, v28
	v_fmac_f32_e32 v23, v40, v40
	v_fmac_f32_e32 v48, v24, v24
	v_fmac_f32_e32 v49, v30, v30
	v_fmamk_f32 v14, v47, 0xba800000, v14
	v_fmac_f32_e32 v12, 0xba800000, v47
	v_mul_f32_e32 v52, v13, v13
	v_mul_f32_e32 v53, v15, v15
	v_fmac_f32_e32 v50, v20, v20
	v_fmac_f32_e32 v51, v26, v26
	v_add_f32_e32 v22, v22, v23
	v_add_f32_e32 v23, v48, v49
	v_fmac_f32_e32 v52, v12, v12
	v_fmac_f32_e32 v53, v14, v14
	v_add_f32_e32 v48, v50, v51
	v_add_f32_e32 v22, v22, v23
	v_add_f32_e32 v49, v52, v53
	v_add_f32_e32 v22, v48, v22
	v_add_f32_e32 v22, v49, v22
	s_nop 1
	v_add_f32_dpp v22, v22, v22 quad_perm:[1,0,3,2] row_mask:0xf bank_mask:0xf bound_ctrl:1
	s_nop 1
	v_add_f32_dpp v22, v22, v22 quad_perm:[2,3,0,1] row_mask:0xf bank_mask:0xf bound_ctrl:1
	s_nop 1
	v_add_f32_dpp v22, v22, v22 row_half_mirror row_mask:0xf bank_mask:0xf bound_ctrl:1
	s_nop 1
	v_add_f32_dpp v22, v22, v22 row_mirror row_mask:0xf bank_mask:0xf bound_ctrl:1
	ds_bpermute_b32 v23, v42, v22
	s_waitcnt lgkmcnt(0)
	v_add_f32_e32 v22, v22, v23
	ds_bpermute_b32 v23, v43, v22
	s_waitcnt lgkmcnt(0)
	v_add_f32_e32 v22, v22, v23
	v_fmamk_f32 v22, v22, 0x3a800000, v44
	v_mul_f32_e32 v23, 0x4f800000, v22
	v_cmp_gt_f32_e32 vcc, s14, v22
	s_nop 1
	v_cndmask_b32_e32 v22, v22, v23, vcc
	v_sqrt_f32_e32 v23, v22
	s_nop 0
	v_add_u32_e32 v48, -1, v23
	v_add_u32_e32 v49, 1, v23
	v_fma_f32 v50, -v48, v23, v22
	v_fma_f32 v51, -v49, v23, v22
	v_cmp_ge_f32_e64 s[6:7], 0, v50
	s_nop 1
	v_cndmask_b32_e64 v23, v23, v48, s[6:7]
	v_cmp_lt_f32_e64 s[6:7], 0, v51
	s_nop 1
	v_cndmask_b32_e64 v23, v23, v49, s[6:7]
	v_mul_f32_e32 v48, 0x37800000, v23
	v_cndmask_b32_e32 v23, v23, v48, vcc
	v_cmp_class_f32_e32 vcc, v22, v45
	s_nop 1
	v_cndmask_b32_e32 v22, v23, v22, vcc
	v_div_scale_f32 v23, s[6:7], v22, v22, 1.0
	v_rcp_f32_e32 v48, v23
	v_div_scale_f32 v49, vcc, 1.0, v22, 1.0
	v_fma_f32 v50, -v23, v48, 1.0
	v_fmac_f32_e32 v48, v50, v48
	v_mul_f32_e32 v50, v49, v48
	v_fma_f32 v51, -v23, v50, v49
	v_fmac_f32_e32 v50, v51, v48
	v_fma_f32 v23, -v23, v50, v49
	v_div_fmas_f32 v23, v23, v48, v50
	v_div_fixup_f32 v22, v23, v22, 1.0
	s_and_saveexec_b64 s[6:7], s[0:1]
	s_cbranch_execz .LBB0_323
	s_ashr_i32 s9, s8, 31
	s_lshl_b64 s[28:29], s[8:9], 2
	s_add_u32 s28, s22, s28
	v_mul_f32_e32 v48, 0x3a800000, v47
	s_addc_u32 s29, s23, s29
	v_mov_b32_e32 v49, v22
	global_store_dwordx2 v46, v[48:49], s[28:29]

; DEV void ln_rows(float* hbuf, bf16* hb, const float* g, const float* bta, float* stats, bool write_h, int gw, int NGW, int lane) {
;     ...
;     for (int m0 = gw; m0 < NTOK; m0 += 2 * NGW) {
;         f32x4 v[2][4]; float s[2];
; #pragma unroll
;         for (int q = 0; q < 2; ++q) { const f32x4* xr = (const f32x4*)(hbuf + (size_t)(m0 + q * NGW) * DM) + lane;
; #pragma unroll
;             for (int j = 0; j < 4; ++j) v[q][j] = xr[64 * j]; }
; #pragma unroll
;         for (int q = 0; q < 2; ++q) { float t = 0.f;
; #pragma unroll
;             for (int j = 0; j < 4; ++j) t += (v[q][j].x + v[q][j].y) + (v[q][j].z + v[q][j].w);
;             s[q] = t; }
; #pragma unroll
;         for (int q = 0; q < 2; ++q) {
;             const int m = m0 + q * NGW;
;             const float mean = wave_sum(s[q], lane) * (1.f / DM); float s2 = 0.f;
; #pragma unroll
;             for (int j = 0; j < 4; ++j) { v[q][j] = v[q][j] - mean; s2 += (v[q][j].x * v[q][j].x + v[q][j].y * v[q][j].y) + (v[q][j].z * v[q][j].z + v[q][j].w * v[q][j].w); }
;             const float rstd = 1.f / sqrtf(wave_sum(s2, lane) * (1.f / DM) + 1e-5f);
;             if (lane == 0) { f32x2_ st2; st2.x = mean; st2.y = rstd; *(f32x2_*)(stats + 2 * m) = st2; }
.LBB0_549:
	s_ashr_i32 s11, s10, 31
	s_lshl_b64 s[6:7], s[10:11], 12
	v_lshl_add_u64 v[0:1], v[32:33], 0, s[6:7]
	global_load_dwordx4 v[28:31], v[0:1], off nt
	global_load_dwordx4 v[24:27], v[0:1], off offset:1024 nt
	global_load_dwordx4 v[20:23], v[0:1], off offset:2048 nt
	global_load_dwordx4 v[12:15], v[0:1], off offset:3072 nt
	s_add_i32 s12, s10, s44
	s_ashr_i32 s13, s12, 31
	s_lshl_b64 s[6:7], s[12:13], 12
	v_lshl_add_u64 v[40:41], v[32:33], 0, s[6:7]
	s_waitcnt vmcnt(3)
	v_mov_b32_e32 v0, v29
	v_mov_b32_e32 v1, v30
	v_mov_b32_e32 v2, v28
	v_mov_b32_e32 v3, v31
	s_waitcnt vmcnt(2)
	v_mov_b32_e32 v4, v25
	v_mov_b32_e32 v5, v26
	v_mov_b32_e32 v6, v24
	v_mov_b32_e32 v7, v27
	v_pk_add_f32 v[0:1], v[0:1], v[2:3]
	v_pk_add_f32 v[2:3], v[4:5], v[6:7]
	v_add_f32_e32 v6, v0, v1
	v_pk_add_f32 v[0:1], v[2:3], v[2:3] op_sel:[0,1] op_sel_hi:[1,0]
	s_waitcnt vmcnt(1)
	v_add_f32_e32 v8, v20, v21
	v_add_f32_e32 v10, v22, v23
	s_waitcnt vmcnt(0)
	v_mov_b32_e32 v17, v12
	v_mov_b32_e32 v9, v14
	v_mov_b32_e32 v11, v15
	v_add_f32_e32 v16, 0, v6
	v_mov_b32_e32 v1, v13
	v_pk_add_f32 v[4:5], v[8:9], v[10:11]
	v_pk_add_f32 v[0:1], v[16:17], v[0:1]
	s_nop 0
	v_pk_add_f32 v[0:1], v[0:1], v[4:5]
	s_nop 0
	v_add_f32_e32 v0, v0, v1
	s_nop 1
	v_add_f32_dpp v0, v0, v0 quad_perm:[1,0,3,2] row_mask:0xf bank_mask:0xf bound_ctrl:1
	s_nop 1
	v_add_f32_dpp v0, v0, v0 quad_perm:[2,3,0,1] row_mask:0xf bank_mask:0xf bound_ctrl:1
	s_nop 1
	v_add_f32_dpp v0, v0, v0 row_half_mirror row_mask:0xf bank_mask:0xf bound_ctrl:1
	s_nop 1
	v_add_f32_dpp v0, v0, v0 row_mirror row_mask:0xf bank_mask:0xf bound_ctrl:1
	ds_bpermute_b32 v1, v42, v0
	s_waitcnt lgkmcnt(0)
	v_add_f32_e32 v47, v0, v1
	global_load_dwordx4 v[16:19], v[40:41], off nt
	global_load_dwordx4 v[8:11], v[40:41], off offset:1024 nt
	global_load_dwordx4 v[4:7], v[40:41], off offset:2048 nt
	global_load_dwordx4 v[0:3], v[40:41], off offset:3072 nt
	ds_bpermute_b32 v48, v43, v47
	s_waitcnt lgkmcnt(0)
	v_add_f32_e32 v47, v47, v48
	v_fmamk_f32 v41, v47, 0xba800000, v31
	v_fmamk_f32 v29, v47, 0xba800000, v29
	v_fmamk_f32 v31, v47, 0xba800000, v27
	v_fmamk_f32 v25, v47, 0xba800000, v25
	v_fmamk_f32 v40, v47, 0xba800000, v30
	v_fmac_f32_e32 v28, 0xba800000, v47
	v_fmamk_f32 v30, v47, 0xba800000, v26
	v_fmac_f32_e32 v24, 0xba800000, v47
	v_fmamk_f32 v27, v47, 0xba800000, v23
	v_fmamk_f32 v26, v47, 0xba800000, v22
	v_fmamk_f32 v21, v47, 0xba800000, v21
	v_mul_f32_e32 v22, v29, v29
	v_mul_f32_e32 v23, v41, v41
	v_mul_f32_e32 v48, v25, v25
	v_mul_f32_e32 v49, v31, v31
	v_fmac_f32_e32 v20, 0xba800000, v47
	v_fmamk_f32 v15, v47, 0xba800000, v15
	v_fmamk_f32 v13, v47, 0xba800000, v13
	v_mul_f32_e32 v50, v21, v21
	v_mul_f32_e32 v51, v27, v27
	v_fmac_f32_e32 v22, v28, v28
	v_fmac_f32_e32 v23, v40, v40
	v_fmac_f32_e32 v48, v24, v24
	v_fmac_f32_e32 v49, v30, v30
	v_fmamk_f32 v14, v47, 0xba800000, v14
	v_fmac_f32_e32 v12, 0xba800000, v47
	v_mul_f32_e32 v52, v13, v13
	v_mul_f32_e32 v53, v15, v15
	v_fmac_f32_e32 v50, v20, v20
	v_fmac_f32_e32 v51, v26, v26
	v_add_f32_e32 v22, v22, v23
	v_add_f32_e32 v23, v48, v49
	v_fmac_f32_e32 v52, v12, v12
	v_fmac_f32_e32 v53, v14, v14
	v_add_f32_e32 v48, v50, v51
	v_add_f32_e32 v22, v22, v23
	v_add_f32_e32 v49, v52, v53
	v_add_f32_e32 v22, v48, v22
	v_add_f32_e32 v22, v49, v22
	s_nop 1
	v_add_f32_dpp v22, v22, v22 quad_perm:[1,0,3,2] row_mask:0xf bank_mask:0xf bound_ctrl:1
	s_nop 1
	v_add_f32_dpp v22, v22, v22 quad_perm:[2,3,0,1] row_mask:0xf bank_mask:0xf bound_ctrl:1
	s_nop 1
	v_add_f32_dpp v22, v22, v22 row_half_mirror row_mask:0xf bank_mask:0xf bound_ctrl:1
	s_nop 1
	v_add_f32_dpp v22, v22, v22 row_mirror row_mask:0xf bank_mask:0xf bound_ctrl:1
	ds_bpermute_b32 v23, v42, v22
	s_waitcnt lgkmcnt(0)
	v_add_f32_e32 v22, v22, v23
	ds_bpermute_b32 v23, v43, v22
	s_waitcnt lgkmcnt(0)
	v_add_f32_e32 v22, v22, v23
	v_fmamk_f32 v22, v22, 0x3a800000, v44
	v_mul_f32_e32 v23, 0x4f800000, v22
	v_cmp_gt_f32_e32 vcc, s18, v22
	s_nop 1
	v_cndmask_b32_e32 v22, v22, v23, vcc
	v_sqrt_f32_e32 v23, v22
	s_nop 0
	v_add_u32_e32 v48, -1, v23
	v_add_u32_e32 v49, 1, v23
	v_fma_f32 v50, -v48, v23, v22
	v_fma_f32 v51, -v49, v23, v22
	v_cmp_ge_f32_e64 s[6:7], 0, v50
	s_nop 1
	v_cndmask_b32_e64 v23, v23, v48, s[6:7]
	v_cmp_lt_f32_e64 s[6:7], 0, v51
	s_nop 1
	v_cndmask_b32_e64 v23, v23, v49, s[6:7]
	v_mul_f32_e32 v48, 0x37800000, v23
	v_cndmask_b32_e32 v23, v23, v48, vcc
	v_cmp_class_f32_e32 vcc, v22, v45
	s_nop 1
	v_cndmask_b32_e32 v22, v23, v22, vcc
	v_div_scale_f32 v23, s[6:7], v22, v22, 1.0
	v_rcp_f32_e32 v48, v23
	v_div_scale_f32 v49, vcc, 1.0, v22, 1.0
	v_fma_f32 v50, -v23, v48, 1.0
	v_fmac_f32_e32 v48, v50, v48
	v_mul_f32_e32 v50, v49, v48
	v_fma_f32 v51, -v23, v50, v49
	v_fmac_f32_e32 v50, v51, v48
	v_fma_f32 v23, -v23, v50, v49
	v_div_fmas_f32 v23, v23, v48, v50
	v_div_fixup_f32 v22, v23, v22, 1.0
	s_and_saveexec_b64 s[6:7], s[0:1]
	s_cbranch_execz .LBB0_551
	s_ashr_i32 s9, s8, 31
	s_lshl_b64 s[20:21], s[8:9], 2
	s_add_u32 s20, s4, s20
	v_mul_f32_e32 v48, 0x3a800000, v47
	s_addc_u32 s21, s5, s21
	v_mov_b32_e32 v49, v22
	global_store_dwordx2 v46, v[48:49], s[20:21]

; DEV void ln_rows(float* hbuf, bf16* hb, const float* g, const float* bta, float* stats, bool write_h, int gw, int NGW, int lane) {
;     ...
;     for (int m0 = gw; m0 < NTOK; m0 += 2 * NGW) {
;         f32x4 v[2][4]; float s[2];
; #pragma unroll
;         for (int q = 0; q < 2; ++q) { const f32x4* xr = (const f32x4*)(hbuf + (size_t)(m0 + q * NGW) * DM) + lane;
; #pragma unroll
;             for (int j = 0; j < 4; ++j) v[q][j] = xr[64 * j]; }
; #pragma unroll
;         for (int q = 0; q < 2; ++q) { float t = 0.f;
; #pragma unroll
;             for (int j = 0; j < 4; ++j) t += (v[q][j].x + v[q][j].y) + (v[q][j].z + v[q][j].w);
;             s[q] = t; }
; #pragma unroll
;         for (int q = 0; q < 2; ++q) {
;             const int m = m0 + q * NGW;
;             const float mean = wave_sum(s[q], lane) * (1.f / DM); float s2 = 0.f;
; #pragma unroll
;             for (int j = 0; j < 4; ++j) { v[q][j] = v[q][j] - mean; s2 += (v[q][j].x * v[q][j].x + v[q][j].y * v[q][j].y) + (v[q][j].z * v[q][j].z + v[q][j].w * v[q][j].w); }
;             const float rstd = 1.f / sqrtf(wave_sum(s2, lane) * (1.f / DM) + 1e-5f);
;             if (lane == 0) { f32x2_ st2; st2.x = mean; st2.y = rstd; *(f32x2_*)(stats + 2 * m) = st2; }
.LBB0_1255:
	s_ashr_i32 s23, s22, 31
	s_lshl_b64 s[6:7], s[22:23], 12
	v_lshl_add_u64 v[0:1], v[32:33], 0, s[6:7]
	global_load_dwordx4 v[28:31], v[0:1], off nt
	global_load_dwordx4 v[24:27], v[0:1], off offset:1024 nt
	global_load_dwordx4 v[20:23], v[0:1], off offset:2048 nt
	global_load_dwordx4 v[12:15], v[0:1], off offset:3072 nt
	s_add_i32 s20, s22, s62
	s_ashr_i32 s21, s20, 31
	s_lshl_b64 s[6:7], s[20:21], 12
	s_waitcnt vmcnt(3)
	v_mov_b32_e32 v0, v29
	v_mov_b32_e32 v1, v30
	v_mov_b32_e32 v2, v28
	v_mov_b32_e32 v3, v31
	s_waitcnt vmcnt(2)
	v_mov_b32_e32 v4, v25
	v_mov_b32_e32 v5, v26
	v_mov_b32_e32 v6, v24
	v_mov_b32_e32 v7, v27
	v_pk_add_f32 v[0:1], v[0:1], v[2:3]
	v_pk_add_f32 v[2:3], v[4:5], v[6:7]
	v_add_f32_e32 v6, v0, v1
	v_pk_add_f32 v[0:1], v[2:3], v[2:3] op_sel:[0,1] op_sel_hi:[1,0]
	s_waitcnt vmcnt(1)
	v_add_f32_e32 v8, v20, v21
	v_add_f32_e32 v10, v22, v23
	s_waitcnt vmcnt(0)
	v_mov_b32_e32 v17, v12
	v_mov_b32_e32 v9, v14
	v_mov_b32_e32 v11, v15
	v_add_f32_e32 v16, 0, v6
	v_mov_b32_e32 v1, v13
	v_pk_add_f32 v[4:5], v[8:9], v[10:11]
	v_pk_add_f32 v[0:1], v[16:17], v[0:1]
	s_nop 0
	v_pk_add_f32 v[0:1], v[0:1], v[4:5]
	s_nop 0
	v_add_f32_e32 v0, v0, v1
	s_nop 1
	v_add_f32_dpp v0, v0, v0 quad_perm:[1,0,3,2] row_mask:0xf bank_mask:0xf bound_ctrl:1
	s_nop 1
	v_add_f32_dpp v0, v0, v0 quad_perm:[2,3,0,1] row_mask:0xf bank_mask:0xf bound_ctrl:1
	s_nop 1
	v_add_f32_dpp v0, v0, v0 row_half_mirror row_mask:0xf bank_mask:0xf bound_ctrl:1
	s_nop 1
	v_add_f32_dpp v2, v0, v0 row_mirror row_mask:0xf bank_mask:0xf bound_ctrl:1
	ds_bpermute_b32 v3, v42, v2
	v_lshl_add_u64 v[0:1], v[32:33], 0, s[6:7]
	s_waitcnt lgkmcnt(0)
	v_add_f32_e32 v40, v2, v3
	global_load_dwordx4 v[16:19], v[0:1], off nt
	global_load_dwordx4 v[8:11], v[0:1], off offset:1024 nt
	global_load_dwordx4 v[4:7], v[0:1], off offset:2048 nt
	s_nop 0
	global_load_dwordx4 v[0:3], v[0:1], off offset:3072 nt
	ds_bpermute_b32 v41, v43, v40
	s_waitcnt lgkmcnt(0)
	v_add_f32_e32 v47, v40, v41
	v_fmamk_f32 v41, v47, 0xba800000, v31
	v_fmamk_f32 v29, v47, 0xba800000, v29
	v_fmamk_f32 v31, v47, 0xba800000, v27
	v_fmamk_f32 v25, v47, 0xba800000, v25
	v_fmamk_f32 v40, v47, 0xba800000, v30
	v_fmac_f32_e32 v28, 0xba800000, v47
	v_fmamk_f32 v30, v47, 0xba800000, v26
	v_fmac_f32_e32 v24, 0xba800000, v47
	v_fmamk_f32 v27, v47, 0xba800000, v23
	v_fmamk_f32 v26, v47, 0xba800000, v22
	v_fmamk_f32 v21, v47, 0xba800000, v21
	v_mul_f32_e32 v22, v29, v29
	v_mul_f32_e32 v23, v41, v41
	v_mul_f32_e32 v48, v25, v25
	v_mul_f32_e32 v49, v31, v31
	v_fmac_f32_e32 v20, 0xba800000, v47
	v_fmamk_f32 v15, v47, 0xba800000, v15
	v_fmamk_f32 v13, v47, 0xba800000, v13
	v_mul_f32_e32 v50, v21, v21
	v_mul_f32_e32 v51, v27, v27
	v_fmac_f32_e32 v22, v28, v28
	v_fmac_f32_e32 v23, v40, v40
	v_fmac_f32_e32 v48, v24, v24
	v_fmac_f32_e32 v49, v30, v30
	v_fmamk_f32 v14, v47, 0xba800000, v14
	v_fmac_f32_e32 v12, 0xba800000, v47
	v_mul_f32_e32 v52, v13, v13
	v_mul_f32_e32 v53, v15, v15
	v_fmac_f32_e32 v50, v20, v20
	v_fmac_f32_e32 v51, v26, v26
	v_add_f32_e32 v22, v22, v23
	v_add_f32_e32 v23, v48, v49
	v_fmac_f32_e32 v52, v12, v12
	v_fmac_f32_e32 v53, v14, v14
	v_add_f32_e32 v48, v50, v51
	v_add_f32_e32 v22, v22, v23
	v_add_f32_e32 v49, v52, v53
	v_add_f32_e32 v22, v48, v22
	v_add_f32_e32 v22, v49, v22
	s_nop 1
	v_add_f32_dpp v22, v22, v22 quad_perm:[1,0,3,2] row_mask:0xf bank_mask:0xf bound_ctrl:1
	s_nop 1
	v_add_f32_dpp v22, v22, v22 quad_perm:[2,3,0,1] row_mask:0xf bank_mask:0xf bound_ctrl:1
	s_nop 1
	v_add_f32_dpp v22, v22, v22 row_half_mirror row_mask:0xf bank_mask:0xf bound_ctrl:1
	s_nop 1
	v_add_f32_dpp v22, v22, v22 row_mirror row_mask:0xf bank_mask:0xf bound_ctrl:1
	ds_bpermute_b32 v23, v42, v22
	s_waitcnt lgkmcnt(0)
	v_add_f32_e32 v22, v22, v23
	ds_bpermute_b32 v23, v43, v22
	s_waitcnt lgkmcnt(0)
	v_add_f32_e32 v22, v22, v23
	v_fmamk_f32 v22, v22, 0x3a800000, v44
	v_mul_f32_e32 v23, 0x4f800000, v22
	v_cmp_gt_f32_e32 vcc, s14, v22
	s_nop 1
	v_cndmask_b32_e32 v22, v22, v23, vcc
	v_sqrt_f32_e32 v23, v22
	s_nop 0
	v_add_u32_e32 v48, -1, v23
	v_add_u32_e32 v49, 1, v23
	v_fma_f32 v50, -v48, v23, v22
	v_fma_f32 v51, -v49, v23, v22
	v_cmp_ge_f32_e64 s[6:7], 0, v50
	s_nop 1
	v_cndmask_b32_e64 v23, v23, v48, s[6:7]
	v_cmp_lt_f32_e64 s[6:7], 0, v51
	s_nop 1
	v_cndmask_b32_e64 v23, v23, v49, s[6:7]
	v_mul_f32_e32 v48, 0x37800000, v23
	v_cndmask_b32_e32 v23, v23, v48, vcc
	v_cmp_class_f32_e32 vcc, v22, v45
	s_nop 1
	v_cndmask_b32_e32 v22, v23, v22, vcc
	v_div_scale_f32 v23, s[6:7], v22, v22, 1.0
	v_rcp_f32_e32 v48, v23
	v_div_scale_f32 v49, vcc, 1.0, v22, 1.0
	v_fma_f32 v50, -v23, v48, 1.0
	v_fmac_f32_e32 v48, v50, v48
	v_mul_f32_e32 v50, v49, v48
	v_fma_f32 v51, -v23, v50, v49
	v_fmac_f32_e32 v50, v51, v48
	v_fma_f32 v23, -v23, v50, v49
	v_div_fmas_f32 v23, v23, v48, v50
	v_div_fixup_f32 v22, v23, v22, 1.0
	s_and_saveexec_b64 s[6:7], s[0:1]
	s_cbranch_execz .LBB0_1257
	s_ashr_i32 s9, s8, 31
	s_lshl_b64 s[24:25], s[8:9], 2
	s_add_u32 s24, s18, s24
	v_mul_f32_e32 v48, 0x3a800000, v47
	s_addc_u32 s25, s19, s25
	v_mov_b32_e32 v49, v22
	global_store_dwordx2 v46, v[48:49], s[24:25]

; DEV void ln_rows(float* hbuf, bf16* hb, const float* g, const float* bta, float* stats, bool write_h, int gw, int NGW, int lane) {
;     ...
;     for (int m0 = gw; m0 < NTOK; m0 += 2 * NGW) {
;         f32x4 v[2][4]; float s[2];
; #pragma unroll
;         for (int q = 0; q < 2; ++q) { const f32x4* xr = (const f32x4*)(hbuf + (size_t)(m0 + q * NGW) * DM) + lane;
; #pragma unroll
;             for (int j = 0; j < 4; ++j) v[q][j] = xr[64 * j]; }
; #pragma unroll
;         for (int q = 0; q < 2; ++q) { float t = 0.f;
; #pragma unroll
;             for (int j = 0; j < 4; ++j) t += (v[q][j].x + v[q][j].y) + (v[q][j].z + v[q][j].w);
;             s[q] = t; }
; #pragma unroll
;         for (int q = 0; q < 2; ++q) {
;             const int m = m0 + q * NGW;
;             const float mean = wave_sum(s[q], lane) * (1.f / DM); float s2 = 0.f;
; #pragma unroll
;             for (int j = 0; j < 4; ++j) { v[q][j] = v[q][j] - mean; s2 += (v[q][j].x * v[q][j].x + v[q][j].y * v[q][j].y) + (v[q][j].z * v[q][j].z + v[q][j].w * v[q][j].w); }
;             const float rstd = 1.f / sqrtf(wave_sum(s2, lane) * (1.f / DM) + 1e-5f);
;             if (lane == 0) { f32x2_ st2; st2.x = mean; st2.y = rstd; *(f32x2_*)(stats + 2 * m) = st2; }
.LBB0_1483:
	s_ashr_i32 s13, s12, 31
	s_lshl_b64 s[6:7], s[12:13], 12
	v_lshl_add_u64 v[0:1], v[32:33], 0, s[6:7]
	global_load_dwordx4 v[28:31], v[0:1], off nt
	global_load_dwordx4 v[24:27], v[0:1], off offset:1024 nt
	global_load_dwordx4 v[20:23], v[0:1], off offset:2048 nt
	global_load_dwordx4 v[12:15], v[0:1], off offset:3072 nt
	s_add_i32 s16, s12, s62
	s_ashr_i32 s17, s16, 31
	s_lshl_b64 s[6:7], s[16:17], 12
	v_lshl_add_u64 v[40:41], v[32:33], 0, s[6:7]
	s_waitcnt vmcnt(3)
	v_mov_b32_e32 v0, v29
	v_mov_b32_e32 v1, v30
	v_mov_b32_e32 v2, v28
	v_mov_b32_e32 v3, v31
	s_waitcnt vmcnt(2)
	v_mov_b32_e32 v4, v25
	v_mov_b32_e32 v5, v26
	v_mov_b32_e32 v6, v24
	v_mov_b32_e32 v7, v27
	v_pk_add_f32 v[0:1], v[0:1], v[2:3]
	v_pk_add_f32 v[2:3], v[4:5], v[6:7]
	v_add_f32_e32 v6, v0, v1
	v_pk_add_f32 v[0:1], v[2:3], v[2:3] op_sel:[0,1] op_sel_hi:[1,0]
	s_waitcnt vmcnt(1)
	v_add_f32_e32 v8, v20, v21
	v_add_f32_e32 v10, v22, v23
	s_waitcnt vmcnt(0)
	v_mov_b32_e32 v17, v12
	v_mov_b32_e32 v9, v14
	v_mov_b32_e32 v11, v15
	v_add_f32_e32 v16, 0, v6
	v_mov_b32_e32 v1, v13
	v_pk_add_f32 v[4:5], v[8:9], v[10:11]
	v_pk_add_f32 v[0:1], v[16:17], v[0:1]
	s_nop 0
	v_pk_add_f32 v[0:1], v[0:1], v[4:5]
	s_nop 0
	v_add_f32_e32 v0, v0, v1
	s_nop 1
	v_add_f32_dpp v0, v0, v0 quad_perm:[1,0,3,2] row_mask:0xf bank_mask:0xf bound_ctrl:1
	s_nop 1
	v_add_f32_dpp v0, v0, v0 quad_perm:[2,3,0,1] row_mask:0xf bank_mask:0xf bound_ctrl:1
	s_nop 1
	v_add_f32_dpp v0, v0, v0 row_half_mirror row_mask:0xf bank_mask:0xf bound_ctrl:1
	s_nop 1
	v_add_f32_dpp v0, v0, v0 row_mirror row_mask:0xf bank_mask:0xf bound_ctrl:1
	ds_bpermute_b32 v1, v42, v0
	s_waitcnt lgkmcnt(0)
	v_add_f32_e32 v47, v0, v1
	global_load_dwordx4 v[16:19], v[40:41], off nt
	global_load_dwordx4 v[8:11], v[40:41], off offset:1024 nt
	global_load_dwordx4 v[4:7], v[40:41], off offset:2048 nt
	global_load_dwordx4 v[0:3], v[40:41], off offset:3072 nt
	ds_bpermute_b32 v48, v43, v47
	s_waitcnt lgkmcnt(0)
	v_add_f32_e32 v47, v47, v48
	v_fmamk_f32 v41, v47, 0xba800000, v31
	v_fmamk_f32 v29, v47, 0xba800000, v29
	v_fmamk_f32 v31, v47, 0xba800000, v27
	v_fmamk_f32 v25, v47, 0xba800000, v25
	v_fmamk_f32 v40, v47, 0xba800000, v30
	v_fmac_f32_e32 v28, 0xba800000, v47
	v_fmamk_f32 v30, v47, 0xba800000, v26
	v_fmac_f32_e32 v24, 0xba800000, v47
	v_fmamk_f32 v27, v47, 0xba800000, v23
	v_fmamk_f32 v26, v47, 0xba800000, v22
	v_fmamk_f32 v21, v47, 0xba800000, v21
	v_mul_f32_e32 v22, v29, v29
	v_mul_f32_e32 v23, v41, v41
	v_mul_f32_e32 v48, v25, v25
	v_mul_f32_e32 v49, v31, v31
	v_fmac_f32_e32 v20, 0xba800000, v47
	v_fmamk_f32 v15, v47, 0xba800000, v15
	v_fmamk_f32 v13, v47, 0xba800000, v13
	v_mul_f32_e32 v50, v21, v21
	v_mul_f32_e32 v51, v27, v27
	v_fmac_f32_e32 v22, v28, v28
	v_fmac_f32_e32 v23, v40, v40
	v_fmac_f32_e32 v48, v24, v24
	v_fmac_f32_e32 v49, v30, v30
	v_fmamk_f32 v14, v47, 0xba800000, v14
	v_fmac_f32_e32 v12, 0xba800000, v47
	v_mul_f32_e32 v52, v13, v13
	v_mul_f32_e32 v53, v15, v15
	v_fmac_f32_e32 v50, v20, v20
	v_fmac_f32_e32 v51, v26, v26
	v_add_f32_e32 v22, v22, v23
	v_add_f32_e32 v23, v48, v49
	v_fmac_f32_e32 v52, v12, v12
	v_fmac_f32_e32 v53, v14, v14
	v_add_f32_e32 v48, v50, v51
	v_add_f32_e32 v22, v22, v23
	v_add_f32_e32 v49, v52, v53
	v_add_f32_e32 v22, v48, v22
	v_add_f32_e32 v22, v49, v22
	s_nop 1
	v_add_f32_dpp v22, v22, v22 quad_perm:[1,0,3,2] row_mask:0xf bank_mask:0xf bound_ctrl:1
	s_nop 1
	v_add_f32_dpp v22, v22, v22 quad_perm:[2,3,0,1] row_mask:0xf bank_mask:0xf bound_ctrl:1
	s_nop 1
	v_add_f32_dpp v22, v22, v22 row_half_mirror row_mask:0xf bank_mask:0xf bound_ctrl:1
	s_nop 1
	v_add_f32_dpp v22, v22, v22 row_mirror row_mask:0xf bank_mask:0xf bound_ctrl:1
	ds_bpermute_b32 v23, v42, v22
	s_waitcnt lgkmcnt(0)
	v_add_f32_e32 v22, v22, v23
	ds_bpermute_b32 v23, v43, v22
	s_waitcnt lgkmcnt(0)
	v_add_f32_e32 v22, v22, v23
	v_fmamk_f32 v22, v22, 0x3a800000, v44
	v_mul_f32_e32 v23, 0x4f800000, v22
	v_cmp_gt_f32_e32 vcc, s14, v22
	s_nop 1
	v_cndmask_b32_e32 v22, v22, v23, vcc
	v_sqrt_f32_e32 v23, v22
	s_nop 0
	v_add_u32_e32 v48, -1, v23
	v_add_u32_e32 v49, 1, v23
	v_fma_f32 v50, -v48, v23, v22
	v_fma_f32 v51, -v49, v23, v22
	v_cmp_ge_f32_e64 s[6:7], 0, v50
	s_nop 1
	v_cndmask_b32_e64 v23, v23, v48, s[6:7]
	v_cmp_lt_f32_e64 s[6:7], 0, v51
	s_nop 1
	v_cndmask_b32_e64 v23, v23, v49, s[6:7]
	v_mul_f32_e32 v48, 0x37800000, v23
	v_cndmask_b32_e32 v23, v23, v48, vcc
	v_cmp_class_f32_e32 vcc, v22, v45
	s_nop 1
	v_cndmask_b32_e32 v22, v23, v22, vcc
	v_div_scale_f32 v23, s[6:7], v22, v22, 1.0
	v_rcp_f32_e32 v48, v23
	v_div_scale_f32 v49, vcc, 1.0, v22, 1.0
	v_fma_f32 v50, -v23, v48, 1.0
	v_fmac_f32_e32 v48, v50, v48
	v_mul_f32_e32 v50, v49, v48
	v_fma_f32 v51, -v23, v50, v49
	v_fmac_f32_e32 v50, v51, v48
	v_fma_f32 v23, -v23, v50, v49
	v_div_fmas_f32 v23, v23, v48, v50
	v_div_fixup_f32 v22, v23, v22, 1.0
	s_and_saveexec_b64 s[6:7], s[0:1]
	s_cbranch_execz .LBB0_1485
	s_ashr_i32 s9, s8, 31
	s_lshl_b64 s[18:19], s[8:9], 2
	s_add_u32 s18, s10, s18
	v_mul_f32_e32 v48, 0x3a800000, v47
	s_addc_u32 s19, s11, s19
	v_mov_b32_e32 v49, v22
	global_store_dwordx2 v46, v[48:49], s[18:19]

; DEV void ln_rows(float* hbuf, bf16* hb, const float* g, const float* bta, float* stats, bool write_h, int gw, int NGW, int lane) {
;     ...
;     for (int m0 = gw; m0 < NTOK; m0 += 2 * NGW) {
;         f32x4 v[2][4]; float s[2];
; #pragma unroll
;         for (int q = 0; q < 2; ++q) { const f32x4* xr = (const f32x4*)(hbuf + (size_t)(m0 + q * NGW) * DM) + lane;
; #pragma unroll
;             for (int j = 0; j < 4; ++j) v[q][j] = xr[64 * j]; }
; #pragma unroll
;         for (int q = 0; q < 2; ++q) { float t = 0.f;
; #pragma unroll
;             for (int j = 0; j < 4; ++j) t += (v[q][j].x + v[q][j].y) + (v[q][j].z + v[q][j].w);
;             s[q] = t; }
; #pragma unroll
;         for (int q = 0; q < 2; ++q) {
;             const int m = m0 + q * NGW;
;             const float mean = wave_sum(s[q], lane) * (1.f / DM); float s2 = 0.f;
; #pragma unroll
;             for (int j = 0; j < 4; ++j) { v[q][j] = v[q][j] - mean; s2 += (v[q][j].x * v[q][j].x + v[q][j].y * v[q][j].y) + (v[q][j].z * v[q][j].z + v[q][j].w * v[q][j].w); }
;             const float rstd = 1.f / sqrtf(wave_sum(s2, lane) * (1.f / DM) + 1e-5f);
;             if (lane == 0) { f32x2_ st2; st2.x = mean; st2.y = rstd; *(f32x2_*)(stats + 2 * m) = st2; }
.LBB0_2010:
	s_ashr_i32 s29, s28, 31
	s_lshl_b64 s[10:11], s[28:29], 12
	v_lshl_add_u64 v[0:1], v[32:33], 0, s[10:11]
	global_load_dwordx4 v[28:31], v[0:1], off nt
	global_load_dwordx4 v[24:27], v[0:1], off offset:1024 nt
	global_load_dwordx4 v[20:23], v[0:1], off offset:2048 nt
	global_load_dwordx4 v[12:15], v[0:1], off offset:3072 nt
	s_add_i32 s26, s28, s62
	s_ashr_i32 s27, s26, 31
	s_lshl_b64 s[10:11], s[26:27], 12
	s_waitcnt vmcnt(3)
	v_mov_b32_e32 v0, v29
	v_mov_b32_e32 v1, v30
	v_mov_b32_e32 v2, v28
	v_mov_b32_e32 v3, v31
	s_waitcnt vmcnt(2)
	v_mov_b32_e32 v4, v25
	v_mov_b32_e32 v5, v26
	v_mov_b32_e32 v6, v24
	v_mov_b32_e32 v7, v27
	v_pk_add_f32 v[0:1], v[0:1], v[2:3]
	v_pk_add_f32 v[2:3], v[4:5], v[6:7]
	v_add_f32_e32 v6, v0, v1
	v_pk_add_f32 v[0:1], v[2:3], v[2:3] op_sel:[0,1] op_sel_hi:[1,0]
	s_waitcnt vmcnt(1)
	v_add_f32_e32 v8, v20, v21
	v_add_f32_e32 v10, v22, v23
	s_waitcnt vmcnt(0)
	v_mov_b32_e32 v17, v12
	v_mov_b32_e32 v9, v14
	v_mov_b32_e32 v11, v15
	v_add_f32_e32 v16, 0, v6
	v_mov_b32_e32 v1, v13
	v_pk_add_f32 v[4:5], v[8:9], v[10:11]
	v_pk_add_f32 v[0:1], v[16:17], v[0:1]
	s_nop 0
	v_pk_add_f32 v[0:1], v[0:1], v[4:5]
	s_nop 0
	v_add_f32_e32 v0, v0, v1
	s_nop 1
	v_add_f32_dpp v0, v0, v0 quad_perm:[1,0,3,2] row_mask:0xf bank_mask:0xf bound_ctrl:1
	s_nop 1
	v_add_f32_dpp v0, v0, v0 quad_perm:[2,3,0,1] row_mask:0xf bank_mask:0xf bound_ctrl:1
	s_nop 1
	v_add_f32_dpp v0, v0, v0 row_half_mirror row_mask:0xf bank_mask:0xf bound_ctrl:1
	s_nop 1
	v_add_f32_dpp v2, v0, v0 row_mirror row_mask:0xf bank_mask:0xf bound_ctrl:1
	ds_bpermute_b32 v3, v42, v2
	v_lshl_add_u64 v[0:1], v[32:33], 0, s[10:11]
	s_waitcnt lgkmcnt(0)
	v_add_f32_e32 v40, v2, v3
	global_load_dwordx4 v[16:19], v[0:1], off nt
	global_load_dwordx4 v[8:11], v[0:1], off offset:1024 nt
	global_load_dwordx4 v[4:7], v[0:1], off offset:2048 nt
	s_nop 0
	global_load_dwordx4 v[0:3], v[0:1], off offset:3072 nt
	ds_bpermute_b32 v41, v43, v40
	s_waitcnt lgkmcnt(0)
	v_add_f32_e32 v47, v40, v41
	v_fmamk_f32 v41, v47, 0xba800000, v31
	v_fmamk_f32 v29, v47, 0xba800000, v29
	v_fmamk_f32 v31, v47, 0xba800000, v27
	v_fmamk_f32 v25, v47, 0xba800000, v25
	v_fmamk_f32 v40, v47, 0xba800000, v30
	v_fmac_f32_e32 v28, 0xba800000, v47
	v_fmamk_f32 v30, v47, 0xba800000, v26
	v_fmac_f32_e32 v24, 0xba800000, v47
	v_fmamk_f32 v27, v47, 0xba800000, v23
	v_fmamk_f32 v26, v47, 0xba800000, v22
	v_fmamk_f32 v21, v47, 0xba800000, v21
	v_mul_f32_e32 v22, v29, v29
	v_mul_f32_e32 v23, v41, v41
	v_mul_f32_e32 v48, v25, v25
	v_mul_f32_e32 v49, v31, v31
	v_fmac_f32_e32 v20, 0xba800000, v47
	v_fmamk_f32 v15, v47, 0xba800000, v15
	v_fmamk_f32 v13, v47, 0xba800000, v13
	v_mul_f32_e32 v50, v21, v21
	v_mul_f32_e32 v51, v27, v27
	v_fmac_f32_e32 v22, v28, v28
	v_fmac_f32_e32 v23, v40, v40
	v_fmac_f32_e32 v48, v24, v24
	v_fmac_f32_e32 v49, v30, v30
	v_fmamk_f32 v14, v47, 0xba800000, v14
	v_fmac_f32_e32 v12, 0xba800000, v47
	v_mul_f32_e32 v52, v13, v13
	v_mul_f32_e32 v53, v15, v15
	v_fmac_f32_e32 v50, v20, v20
	v_fmac_f32_e32 v51, v26, v26
	v_add_f32_e32 v22, v22, v23
	v_add_f32_e32 v23, v48, v49
	v_fmac_f32_e32 v52, v12, v12
	v_fmac_f32_e32 v53, v14, v14
	v_add_f32_e32 v48, v50, v51
	v_add_f32_e32 v22, v22, v23
	v_add_f32_e32 v49, v52, v53
	v_add_f32_e32 v22, v48, v22
	v_add_f32_e32 v22, v49, v22
	s_nop 1
	v_add_f32_dpp v22, v22, v22 quad_perm:[1,0,3,2] row_mask:0xf bank_mask:0xf bound_ctrl:1
	s_nop 1
	v_add_f32_dpp v22, v22, v22 quad_perm:[2,3,0,1] row_mask:0xf bank_mask:0xf bound_ctrl:1
	s_nop 1
	v_add_f32_dpp v22, v22, v22 row_half_mirror row_mask:0xf bank_mask:0xf bound_ctrl:1
	s_nop 1
	v_add_f32_dpp v22, v22, v22 row_mirror row_mask:0xf bank_mask:0xf bound_ctrl:1
	ds_bpermute_b32 v23, v42, v22
	s_waitcnt lgkmcnt(0)
	v_add_f32_e32 v22, v22, v23
	ds_bpermute_b32 v23, v43, v22
	s_waitcnt lgkmcnt(0)
	v_add_f32_e32 v22, v22, v23
	v_fmamk_f32 v22, v22, 0x3a800000, v44
	v_mul_f32_e32 v23, 0x4f800000, v22
	v_cmp_gt_f32_e32 vcc, s14, v22
	s_nop 1
	v_cndmask_b32_e32 v22, v22, v23, vcc
	v_sqrt_f32_e32 v23, v22
	s_nop 0
	v_add_u32_e32 v48, -1, v23
	v_add_u32_e32 v49, 1, v23
	v_fma_f32 v50, -v48, v23, v22
	v_fma_f32 v51, -v49, v23, v22
	v_cmp_ge_f32_e64 s[10:11], 0, v50
	s_nop 1
	v_cndmask_b32_e64 v23, v23, v48, s[10:11]
	v_cmp_lt_f32_e64 s[10:11], 0, v51
	s_nop 1
	v_cndmask_b32_e64 v23, v23, v49, s[10:11]
	v_mul_f32_e32 v48, 0x37800000, v23
	v_cndmask_b32_e32 v23, v23, v48, vcc
	v_cmp_class_f32_e32 vcc, v22, v45
	s_nop 1
	v_cndmask_b32_e32 v22, v23, v22, vcc
	v_div_scale_f32 v23, s[10:11], v22, v22, 1.0
	v_rcp_f32_e32 v48, v23
	v_div_scale_f32 v49, vcc, 1.0, v22, 1.0
	v_fma_f32 v50, -v23, v48, 1.0
	v_fmac_f32_e32 v48, v50, v48
	v_mul_f32_e32 v50, v49, v48
	v_fma_f32 v51, -v23, v50, v49
	v_fmac_f32_e32 v50, v51, v48
	v_fma_f32 v23, -v23, v50, v49
	v_div_fmas_f32 v23, v23, v48, v50
	v_div_fixup_f32 v22, v23, v22, 1.0
	s_and_saveexec_b64 s[10:11], s[0:1]
	s_cbranch_execz .LBB0_2012
	s_ashr_i32 s13, s12, 31
	s_lshl_b64 s[30:31], s[12:13], 2
	s_add_u32 s30, s24, s30
	v_mul_f32_e32 v48, 0x3a800000, v47
	s_addc_u32 s31, s25, s31
	v_mov_b32_e32 v49, v22
	global_store_dwordx2 v46, v[48:49], s[30:31]

; DEV void ln_rows(float* hbuf, bf16* hb, const float* g, const float* bta, float* stats, bool write_h, int gw, int NGW, int lane) {
;     ...
;     for (int m0 = gw; m0 < NTOK; m0 += 2 * NGW) {
;         f32x4 v[2][4]; float s[2];
; #pragma unroll
;         for (int q = 0; q < 2; ++q) { const f32x4* xr = (const f32x4*)(hbuf + (size_t)(m0 + q * NGW) * DM) + lane;
; #pragma unroll
;             for (int j = 0; j < 4; ++j) v[q][j] = xr[64 * j]; }
; #pragma unroll
;         for (int q = 0; q < 2; ++q) { float t = 0.f;
; #pragma unroll
;             for (int j = 0; j < 4; ++j) t += (v[q][j].x + v[q][j].y) + (v[q][j].z + v[q][j].w);
;             s[q] = t; }
; #pragma unroll
;         for (int q = 0; q < 2; ++q) {
;             const int m = m0 + q * NGW;
;             const float mean = wave_sum(s[q], lane) * (1.f / DM); float s2 = 0.f;
; #pragma unroll
;             for (int j = 0; j < 4; ++j) { v[q][j] = v[q][j] - mean; s2 += (v[q][j].x * v[q][j].x + v[q][j].y * v[q][j].y) + (v[q][j].z * v[q][j].z + v[q][j].w * v[q][j].w); }
;             const float rstd = 1.f / sqrtf(wave_sum(s2, lane) * (1.f / DM) + 1e-5f);
;             if (lane == 0) { f32x2_ st2; st2.x = mean; st2.y = rstd; *(f32x2_*)(stats + 2 * m) = st2; }
.LBB0_2238:
	s_ashr_i32 s21, s20, 31
	s_lshl_b64 s[8:9], s[20:21], 12
	v_lshl_add_u64 v[0:1], v[32:33], 0, s[8:9]
	global_load_dwordx4 v[28:31], v[0:1], off nt
	global_load_dwordx4 v[24:27], v[0:1], off offset:1024 nt
	global_load_dwordx4 v[20:23], v[0:1], off offset:2048 nt
	global_load_dwordx4 v[12:15], v[0:1], off offset:3072 nt
	s_add_i32 s12, s20, s62
	s_ashr_i32 s13, s12, 31
	s_lshl_b64 s[8:9], s[12:13], 12
	v_lshl_add_u64 v[40:41], v[32:33], 0, s[8:9]
	s_waitcnt vmcnt(3)
	v_mov_b32_e32 v0, v29
	v_mov_b32_e32 v1, v30
	v_mov_b32_e32 v2, v28
	v_mov_b32_e32 v3, v31
	s_waitcnt vmcnt(2)
	v_mov_b32_e32 v4, v25
	v_mov_b32_e32 v5, v26
	v_mov_b32_e32 v6, v24
	v_mov_b32_e32 v7, v27
	v_pk_add_f32 v[0:1], v[0:1], v[2:3]
	v_pk_add_f32 v[2:3], v[4:5], v[6:7]
	v_add_f32_e32 v6, v0, v1
	v_pk_add_f32 v[0:1], v[2:3], v[2:3] op_sel:[0,1] op_sel_hi:[1,0]
	s_waitcnt vmcnt(1)
	v_add_f32_e32 v8, v20, v21
	v_add_f32_e32 v10, v22, v23
	s_waitcnt vmcnt(0)
	v_mov_b32_e32 v17, v12
	v_mov_b32_e32 v9, v14
	v_mov_b32_e32 v11, v15
	v_add_f32_e32 v16, 0, v6
	v_mov_b32_e32 v1, v13
	v_pk_add_f32 v[4:5], v[8:9], v[10:11]
	v_pk_add_f32 v[0:1], v[16:17], v[0:1]
	s_nop 0
	v_pk_add_f32 v[0:1], v[0:1], v[4:5]
	s_nop 0
	v_add_f32_e32 v0, v0, v1
	s_nop 1
	v_add_f32_dpp v0, v0, v0 quad_perm:[1,0,3,2] row_mask:0xf bank_mask:0xf bound_ctrl:1
	s_nop 1
	v_add_f32_dpp v0, v0, v0 quad_perm:[2,3,0,1] row_mask:0xf bank_mask:0xf bound_ctrl:1
	s_nop 1
	v_add_f32_dpp v0, v0, v0 row_half_mirror row_mask:0xf bank_mask:0xf bound_ctrl:1
	s_nop 1
	v_add_f32_dpp v0, v0, v0 row_mirror row_mask:0xf bank_mask:0xf bound_ctrl:1
	ds_bpermute_b32 v1, v42, v0
	s_waitcnt lgkmcnt(0)
	v_add_f32_e32 v47, v0, v1
	global_load_dwordx4 v[16:19], v[40:41], off nt
	global_load_dwordx4 v[8:11], v[40:41], off offset:1024 nt
	global_load_dwordx4 v[4:7], v[40:41], off offset:2048 nt
	global_load_dwordx4 v[0:3], v[40:41], off offset:3072 nt
	ds_bpermute_b32 v48, v43, v47
	s_waitcnt lgkmcnt(0)
	v_add_f32_e32 v47, v47, v48
	v_fmamk_f32 v41, v47, 0xba800000, v31
	v_fmamk_f32 v29, v47, 0xba800000, v29
	v_fmamk_f32 v31, v47, 0xba800000, v27
	v_fmamk_f32 v25, v47, 0xba800000, v25
	v_fmamk_f32 v40, v47, 0xba800000, v30
	v_fmac_f32_e32 v28, 0xba800000, v47
	v_fmamk_f32 v30, v47, 0xba800000, v26
	v_fmac_f32_e32 v24, 0xba800000, v47
	v_fmamk_f32 v27, v47, 0xba800000, v23
	v_fmamk_f32 v26, v47, 0xba800000, v22
	v_fmamk_f32 v21, v47, 0xba800000, v21
	v_mul_f32_e32 v22, v29, v29
	v_mul_f32_e32 v23, v41, v41
	v_mul_f32_e32 v48, v25, v25
	v_mul_f32_e32 v49, v31, v31
	v_fmac_f32_e32 v20, 0xba800000, v47
	v_fmamk_f32 v15, v47, 0xba800000, v15
	v_fmamk_f32 v13, v47, 0xba800000, v13
	v_mul_f32_e32 v50, v21, v21
	v_mul_f32_e32 v51, v27, v27
	v_fmac_f32_e32 v22, v28, v28
	v_fmac_f32_e32 v23, v40, v40
	v_fmac_f32_e32 v48, v24, v24
	v_fmac_f32_e32 v49, v30, v30
	v_fmamk_f32 v14, v47, 0xba800000, v14
	v_fmac_f32_e32 v12, 0xba800000, v47
	v_mul_f32_e32 v52, v13, v13
	v_mul_f32_e32 v53, v15, v15
	v_fmac_f32_e32 v50, v20, v20
	v_fmac_f32_e32 v51, v26, v26
	v_add_f32_e32 v22, v22, v23
	v_add_f32_e32 v23, v48, v49
	v_fmac_f32_e32 v52, v12, v12
	v_fmac_f32_e32 v53, v14, v14
	v_add_f32_e32 v48, v50, v51
	v_add_f32_e32 v22, v22, v23
	v_add_f32_e32 v49, v52, v53
	v_add_f32_e32 v22, v48, v22
	v_add_f32_e32 v22, v49, v22
	s_nop 1
	v_add_f32_dpp v22, v22, v22 quad_perm:[1,0,3,2] row_mask:0xf bank_mask:0xf bound_ctrl:1
	s_nop 1
	v_add_f32_dpp v22, v22, v22 quad_perm:[2,3,0,1] row_mask:0xf bank_mask:0xf bound_ctrl:1
	s_nop 1
	v_add_f32_dpp v22, v22, v22 row_half_mirror row_mask:0xf bank_mask:0xf bound_ctrl:1
	s_nop 1
	v_add_f32_dpp v22, v22, v22 row_mirror row_mask:0xf bank_mask:0xf bound_ctrl:1
	ds_bpermute_b32 v23, v42, v22
	s_waitcnt lgkmcnt(0)
	v_add_f32_e32 v22, v22, v23
	ds_bpermute_b32 v23, v43, v22
	s_waitcnt lgkmcnt(0)
	v_add_f32_e32 v22, v22, v23
	v_fmamk_f32 v22, v22, 0x3a800000, v44
	v_mul_f32_e32 v23, 0x4f800000, v22
	v_cmp_gt_f32_e32 vcc, s14, v22
	s_nop 1
	v_cndmask_b32_e32 v22, v22, v23, vcc
	v_sqrt_f32_e32 v23, v22
	s_nop 0
	v_add_u32_e32 v48, -1, v23
	v_add_u32_e32 v49, 1, v23
	v_fma_f32 v50, -v48, v23, v22
	v_fma_f32 v51, -v49, v23, v22
	v_cmp_ge_f32_e64 s[8:9], 0, v50
	s_nop 1
	v_cndmask_b32_e64 v23, v23, v48, s[8:9]
	v_cmp_lt_f32_e64 s[8:9], 0, v51
	s_nop 1
	v_cndmask_b32_e64 v23, v23, v49, s[8:9]
	v_mul_f32_e32 v48, 0x37800000, v23
	v_cndmask_b32_e32 v23, v23, v48, vcc
	v_cmp_class_f32_e32 vcc, v22, v45
	s_nop 1
	v_cndmask_b32_e32 v22, v23, v22, vcc
	v_div_scale_f32 v23, s[8:9], v22, v22, 1.0
	v_rcp_f32_e32 v48, v23
	v_div_scale_f32 v49, vcc, 1.0, v22, 1.0
	v_fma_f32 v50, -v23, v48, 1.0
	v_fmac_f32_e32 v48, v50, v48
	v_mul_f32_e32 v50, v49, v48
	v_fma_f32 v51, -v23, v50, v49
	v_fmac_f32_e32 v50, v51, v48
	v_fma_f32 v23, -v23, v50, v49
	v_div_fmas_f32 v23, v23, v48, v50
	v_div_fixup_f32 v22, v23, v22, 1.0
	s_and_saveexec_b64 s[8:9], s[0:1]
	s_cbranch_execz .LBB0_2240
	s_ashr_i32 s11, s10, 31
	s_lshl_b64 s[16:17], s[10:11], 2
	s_add_u32 s16, s22, s16
	v_mul_f32_e32 v48, 0x3a800000, v47
	s_addc_u32 s17, s23, s17
	v_mov_b32_e32 v49, v22
	global_store_dwordx2 v46, v[48:49], s[16:17]

; DEV void ln_rows(float* hbuf, bf16* hb, const float* g, const float* bta, float* stats, bool write_h, int gw, int NGW, int lane) {
;     ...
;     for (int m0 = gw; m0 < NTOK; m0 += 2 * NGW) {
;         f32x4 v[2][4]; float s[2];
; #pragma unroll
;         for (int q = 0; q < 2; ++q) { const f32x4* xr = (const f32x4*)(hbuf + (size_t)(m0 + q * NGW) * DM) + lane;
; #pragma unroll
;             for (int j = 0; j < 4; ++j) v[q][j] = xr[64 * j]; }
; #pragma unroll
;         for (int q = 0; q < 2; ++q) { float t = 0.f;
; #pragma unroll
;             for (int j = 0; j < 4; ++j) t += (v[q][j].x + v[q][j].y) + (v[q][j].z + v[q][j].w);
;             s[q] = t; }
; #pragma unroll
;         for (int q = 0; q < 2; ++q) {
;             const int m = m0 + q * NGW;
;             const float mean = wave_sum(s[q], lane) * (1.f / DM); float s2 = 0.f;
; #pragma unroll
;             for (int j = 0; j < 4; ++j) { v[q][j] = v[q][j] - mean; s2 += (v[q][j].x * v[q][j].x + v[q][j].y * v[q][j].y) + (v[q][j].z * v[q][j].z + v[q][j].w * v[q][j].w); }
;             const float rstd = 1.f / sqrtf(wave_sum(s2, lane) * (1.f / DM) + 1e-5f);
;             if (lane == 0) { f32x2_ st2; st2.x = mean; st2.y = rstd; *(f32x2_*)(stats + 2 * m) = st2; }
.LBB0_3039:
	s_ashr_i32 s27, s26, 31
	s_lshl_b64 s[6:7], s[26:27], 12
	v_lshl_add_u64 v[0:1], v[32:33], 0, s[6:7]
	global_load_dwordx4 v[28:31], v[0:1], off nt
	global_load_dwordx4 v[24:27], v[0:1], off offset:1024 nt
	global_load_dwordx4 v[20:23], v[0:1], off offset:2048 nt
	global_load_dwordx4 v[12:15], v[0:1], off offset:3072 nt
	s_add_i32 s24, s26, s54
	s_ashr_i32 s25, s24, 31
	s_lshl_b64 s[6:7], s[24:25], 12
	v_lshl_add_u64 v[40:41], v[32:33], 0, s[6:7]
	s_waitcnt vmcnt(3)
	v_mov_b32_e32 v0, v29
	v_mov_b32_e32 v1, v30
	v_mov_b32_e32 v2, v28
	v_mov_b32_e32 v3, v31
	s_waitcnt vmcnt(2)
	v_mov_b32_e32 v4, v25
	v_mov_b32_e32 v5, v26
	v_mov_b32_e32 v6, v24
	v_mov_b32_e32 v7, v27
	v_pk_add_f32 v[0:1], v[0:1], v[2:3]
	v_pk_add_f32 v[2:3], v[4:5], v[6:7]
	v_add_f32_e32 v6, v0, v1
	v_pk_add_f32 v[0:1], v[2:3], v[2:3] op_sel:[0,1] op_sel_hi:[1,0]
	s_waitcnt vmcnt(1)
	v_add_f32_e32 v8, v20, v21
	v_add_f32_e32 v10, v22, v23
	s_waitcnt vmcnt(0)
	v_mov_b32_e32 v17, v12
	v_mov_b32_e32 v9, v14
	v_mov_b32_e32 v11, v15
	v_add_f32_e32 v16, 0, v6
	v_mov_b32_e32 v1, v13
	v_pk_add_f32 v[4:5], v[8:9], v[10:11]
	v_pk_add_f32 v[0:1], v[16:17], v[0:1]
	s_nop 0
	v_pk_add_f32 v[0:1], v[0:1], v[4:5]
	s_nop 0
	v_add_f32_e32 v0, v0, v1
	s_nop 1
	v_add_f32_dpp v0, v0, v0 quad_perm:[1,0,3,2] row_mask:0xf bank_mask:0xf bound_ctrl:1
	s_nop 1
	v_add_f32_dpp v0, v0, v0 quad_perm:[2,3,0,1] row_mask:0xf bank_mask:0xf bound_ctrl:1
	s_nop 1
	v_add_f32_dpp v0, v0, v0 row_half_mirror row_mask:0xf bank_mask:0xf bound_ctrl:1
	s_nop 1
	v_add_f32_dpp v0, v0, v0 row_mirror row_mask:0xf bank_mask:0xf bound_ctrl:1
	ds_bpermute_b32 v1, v42, v0
	s_waitcnt lgkmcnt(0)
	v_add_f32_e32 v47, v0, v1
	global_load_dwordx4 v[16:19], v[40:41], off nt
	global_load_dwordx4 v[8:11], v[40:41], off offset:1024 nt
	global_load_dwordx4 v[4:7], v[40:41], off offset:2048 nt
	global_load_dwordx4 v[0:3], v[40:41], off offset:3072 nt
	ds_bpermute_b32 v48, v43, v47
	s_waitcnt lgkmcnt(0)
	v_add_f32_e32 v47, v47, v48
	v_fmamk_f32 v41, v47, 0xba800000, v31
	v_fmamk_f32 v29, v47, 0xba800000, v29
	v_fmamk_f32 v31, v47, 0xba800000, v27
	v_fmamk_f32 v25, v47, 0xba800000, v25
	v_fmamk_f32 v40, v47, 0xba800000, v30
	v_fmac_f32_e32 v28, 0xba800000, v47
	v_fmamk_f32 v30, v47, 0xba800000, v26
	v_fmac_f32_e32 v24, 0xba800000, v47
	v_fmamk_f32 v27, v47, 0xba800000, v23
	v_fmamk_f32 v26, v47, 0xba800000, v22
	v_fmamk_f32 v21, v47, 0xba800000, v21
	v_mul_f32_e32 v22, v29, v29
	v_mul_f32_e32 v23, v41, v41
	v_mul_f32_e32 v48, v25, v25
	v_mul_f32_e32 v49, v31, v31
	v_fmac_f32_e32 v20, 0xba800000, v47
	v_fmamk_f32 v15, v47, 0xba800000, v15
	v_fmamk_f32 v13, v47, 0xba800000, v13
	v_mul_f32_e32 v50, v21, v21
	v_mul_f32_e32 v51, v27, v27
	v_fmac_f32_e32 v22, v28, v28
	v_fmac_f32_e32 v23, v40, v40
	v_fmac_f32_e32 v48, v24, v24
	v_fmac_f32_e32 v49, v30, v30
	v_fmamk_f32 v14, v47, 0xba800000, v14
	v_fmac_f32_e32 v12, 0xba800000, v47
	v_mul_f32_e32 v52, v13, v13
	v_mul_f32_e32 v53, v15, v15
	v_fmac_f32_e32 v50, v20, v20
	v_fmac_f32_e32 v51, v26, v26
	v_add_f32_e32 v22, v22, v23
	v_add_f32_e32 v23, v48, v49
	v_fmac_f32_e32 v52, v12, v12
	v_fmac_f32_e32 v53, v14, v14
	v_add_f32_e32 v48, v50, v51
	v_add_f32_e32 v22, v22, v23
	v_add_f32_e32 v49, v52, v53
	v_add_f32_e32 v22, v48, v22
	v_add_f32_e32 v22, v49, v22
	s_nop 1
	v_add_f32_dpp v22, v22, v22 quad_perm:[1,0,3,2] row_mask:0xf bank_mask:0xf bound_ctrl:1
	s_nop 1
	v_add_f32_dpp v22, v22, v22 quad_perm:[2,3,0,1] row_mask:0xf bank_mask:0xf bound_ctrl:1
	s_nop 1
	v_add_f32_dpp v22, v22, v22 row_half_mirror row_mask:0xf bank_mask:0xf bound_ctrl:1
	s_nop 1
	v_add_f32_dpp v22, v22, v22 row_mirror row_mask:0xf bank_mask:0xf bound_ctrl:1
	ds_bpermute_b32 v23, v42, v22
	s_waitcnt lgkmcnt(0)
	v_add_f32_e32 v22, v22, v23
	ds_bpermute_b32 v23, v43, v22
	s_waitcnt lgkmcnt(0)
	v_add_f32_e32 v22, v22, v23
	v_fmamk_f32 v22, v22, 0x3a800000, v44
	v_mul_f32_e32 v23, 0x4f800000, v22
	v_cmp_gt_f32_e32 vcc, s14, v22
	s_nop 1
	v_cndmask_b32_e32 v22, v22, v23, vcc
	v_sqrt_f32_e32 v23, v22
	s_nop 0
	v_add_u32_e32 v48, -1, v23
	v_add_u32_e32 v49, 1, v23
	v_fma_f32 v50, -v48, v23, v22
	v_fma_f32 v51, -v49, v23, v22
	v_cmp_ge_f32_e64 s[6:7], 0, v50
	s_nop 1
	v_cndmask_b32_e64 v23, v23, v48, s[6:7]
	v_cmp_lt_f32_e64 s[6:7], 0, v51
	s_nop 1
	v_cndmask_b32_e64 v23, v23, v49, s[6:7]
	v_mul_f32_e32 v48, 0x37800000, v23
	v_cndmask_b32_e32 v23, v23, v48, vcc
	v_cmp_class_f32_e32 vcc, v22, v45
	s_nop 1
	v_cndmask_b32_e32 v22, v23, v22, vcc
	v_div_scale_f32 v23, s[6:7], v22, v22, 1.0
	v_rcp_f32_e32 v48, v23
	v_div_scale_f32 v49, vcc, 1.0, v22, 1.0
	v_fma_f32 v50, -v23, v48, 1.0
	v_fmac_f32_e32 v48, v50, v48
	v_mul_f32_e32 v50, v49, v48
	v_fma_f32 v51, -v23, v50, v49
	v_fmac_f32_e32 v50, v51, v48
	v_fma_f32 v23, -v23, v50, v49
	v_div_fmas_f32 v23, v23, v48, v50
	v_div_fixup_f32 v22, v23, v22, 1.0
	s_and_saveexec_b64 s[6:7], s[0:1]
	s_cbranch_execz .LBB0_3041
	s_ashr_i32 s23, s22, 31
	s_lshl_b64 s[12:13], s[22:23], 2
	s_add_u32 s12, s20, s12
	v_mul_f32_e32 v48, 0x3a800000, v47
	s_addc_u32 s13, s21, s13
	v_mov_b32_e32 v49, v22
	global_store_dwordx2 v46, v[48:49], s[12:13]

; DEV void ln_rows(float* hbuf, bf16* hb, const float* g, const float* bta, float* stats, bool write_h, int gw, int NGW, int lane) {
;     ...
;     for (int m0 = gw; m0 < NTOK; m0 += 2 * NGW) {
;         f32x4 v[2][4]; float s[2];
; #pragma unroll
;         for (int q = 0; q < 2; ++q) { const f32x4* xr = (const f32x4*)(hbuf + (size_t)(m0 + q * NGW) * DM) + lane;
; #pragma unroll
;             for (int j = 0; j < 4; ++j) v[q][j] = xr[64 * j]; }
; #pragma unroll
;         for (int q = 0; q < 2; ++q) { float t = 0.f;
; #pragma unroll
;             for (int j = 0; j < 4; ++j) t += (v[q][j].x + v[q][j].y) + (v[q][j].z + v[q][j].w);
;             s[q] = t; }
; #pragma unroll
;         for (int q = 0; q < 2; ++q) {
;             const int m = m0 + q * NGW;
;             const float mean = wave_sum(s[q], lane) * (1.f / DM); float s2 = 0.f;
; #pragma unroll
;             for (int j = 0; j < 4; ++j) { v[q][j] = v[q][j] - mean; s2 += (v[q][j].x * v[q][j].x + v[q][j].y * v[q][j].y) + (v[q][j].z * v[q][j].z + v[q][j].w * v[q][j].w); }
;             const float rstd = 1.f / sqrtf(wave_sum(s2, lane) * (1.f / DM) + 1e-5f);
;             if (lane == 0) { f32x2_ st2; st2.x = mean; st2.y = rstd; *(f32x2_*)(stats + 2 * m) = st2; }
.LBB0_3267:
	s_ashr_i32 s9, s8, 31
	s_lshl_b64 s[2:3], s[8:9], 12
	v_lshl_add_u64 v[42:43], v[32:33], 0, s[2:3]
	global_load_dwordx4 v[28:31], v[42:43], off nt
	global_load_dwordx4 v[24:27], v[42:43], off offset:1024 nt
	global_load_dwordx4 v[20:23], v[42:43], off offset:2048 nt
	global_load_dwordx4 v[12:15], v[42:43], off offset:3072 nt
	s_add_i32 s6, s8, s54
	s_ashr_i32 s7, s6, 31
	s_lshl_b64 s[2:3], s[6:7], 12
	v_lshl_add_u64 v[40:41], v[32:33], 0, s[2:3]
	s_waitcnt vmcnt(3)
	v_mov_b32_e32 v0, v29
	v_mov_b32_e32 v1, v30
	v_mov_b32_e32 v2, v28
	v_mov_b32_e32 v3, v31
	s_waitcnt vmcnt(2)
	v_mov_b32_e32 v4, v25
	v_mov_b32_e32 v5, v26
	v_mov_b32_e32 v6, v24
	v_mov_b32_e32 v7, v27
	v_pk_add_f32 v[0:1], v[0:1], v[2:3]
	v_pk_add_f32 v[2:3], v[4:5], v[6:7]
	v_add_f32_e32 v6, v0, v1
	v_pk_add_f32 v[0:1], v[2:3], v[2:3] op_sel:[0,1] op_sel_hi:[1,0]
	s_waitcnt vmcnt(1)
	v_add_f32_e32 v8, v20, v21
	v_add_f32_e32 v10, v22, v23
	s_waitcnt vmcnt(0)
	v_mov_b32_e32 v17, v12
	v_mov_b32_e32 v9, v14
	v_mov_b32_e32 v11, v15
	v_add_f32_e32 v16, 0, v6
	v_mov_b32_e32 v1, v13
	v_pk_add_f32 v[4:5], v[8:9], v[10:11]
	v_pk_add_f32 v[0:1], v[16:17], v[0:1]
	s_nop 0
	v_pk_add_f32 v[0:1], v[0:1], v[4:5]
	s_nop 0
	v_add_f32_e32 v0, v0, v1
	s_nop 1
	v_add_f32_dpp v0, v0, v0 quad_perm:[1,0,3,2] row_mask:0xf bank_mask:0xf bound_ctrl:1
	s_nop 1
	v_add_f32_dpp v0, v0, v0 quad_perm:[2,3,0,1] row_mask:0xf bank_mask:0xf bound_ctrl:1
	s_nop 1
	v_add_f32_dpp v0, v0, v0 row_half_mirror row_mask:0xf bank_mask:0xf bound_ctrl:1
	s_nop 1
	v_add_f32_dpp v0, v0, v0 row_mirror row_mask:0xf bank_mask:0xf bound_ctrl:1
	ds_bpermute_b32 v1, v46, v0
	s_waitcnt lgkmcnt(0)
	v_add_f32_e32 v44, v0, v1
	global_load_dwordx4 v[16:19], v[40:41], off nt
	global_load_dwordx4 v[8:11], v[40:41], off offset:1024 nt
	global_load_dwordx4 v[4:7], v[40:41], off offset:2048 nt
	global_load_dwordx4 v[0:3], v[40:41], off offset:3072 nt
	ds_bpermute_b32 v45, v47, v44
	s_waitcnt lgkmcnt(0)
	v_add_f32_e32 v51, v44, v45
	v_fmamk_f32 v45, v51, 0xba800000, v31
	v_fmamk_f32 v29, v51, 0xba800000, v29
	v_fmamk_f32 v31, v51, 0xba800000, v27
	v_fmamk_f32 v25, v51, 0xba800000, v25
	v_fmamk_f32 v44, v51, 0xba800000, v30
	v_fmac_f32_e32 v28, 0xba800000, v51
	v_fmamk_f32 v30, v51, 0xba800000, v26
	v_fmac_f32_e32 v24, 0xba800000, v51
	v_fmamk_f32 v27, v51, 0xba800000, v23
	v_fmamk_f32 v26, v51, 0xba800000, v22
	v_fmamk_f32 v21, v51, 0xba800000, v21
	v_mul_f32_e32 v22, v29, v29
	v_mul_f32_e32 v23, v45, v45
	v_mul_f32_e32 v52, v25, v25
	v_mul_f32_e32 v53, v31, v31
	v_fmac_f32_e32 v20, 0xba800000, v51
	v_fmamk_f32 v15, v51, 0xba800000, v15
	v_fmamk_f32 v13, v51, 0xba800000, v13
	v_mul_f32_e32 v54, v21, v21
	v_mul_f32_e32 v55, v27, v27
	v_fmac_f32_e32 v22, v28, v28
	v_fmac_f32_e32 v23, v44, v44
	v_fmac_f32_e32 v52, v24, v24
	v_fmac_f32_e32 v53, v30, v30
	v_fmamk_f32 v14, v51, 0xba800000, v14
	v_fmac_f32_e32 v12, 0xba800000, v51
	v_mul_f32_e32 v56, v13, v13
	v_mul_f32_e32 v57, v15, v15
	v_fmac_f32_e32 v54, v20, v20
	v_fmac_f32_e32 v55, v26, v26
	v_add_f32_e32 v22, v22, v23
	v_add_f32_e32 v23, v52, v53
	v_fmac_f32_e32 v56, v12, v12
	v_fmac_f32_e32 v57, v14, v14
	v_add_f32_e32 v52, v54, v55
	v_add_f32_e32 v22, v22, v23
	v_add_f32_e32 v53, v56, v57
	v_add_f32_e32 v22, v52, v22
	v_add_f32_e32 v22, v53, v22
	s_nop 1
	v_add_f32_dpp v22, v22, v22 quad_perm:[1,0,3,2] row_mask:0xf bank_mask:0xf bound_ctrl:1
	s_nop 1
	v_add_f32_dpp v22, v22, v22 quad_perm:[2,3,0,1] row_mask:0xf bank_mask:0xf bound_ctrl:1
	s_nop 1
	v_add_f32_dpp v22, v22, v22 row_half_mirror row_mask:0xf bank_mask:0xf bound_ctrl:1
	s_nop 1
	v_add_f32_dpp v22, v22, v22 row_mirror row_mask:0xf bank_mask:0xf bound_ctrl:1
	ds_bpermute_b32 v23, v46, v22
	s_waitcnt lgkmcnt(0)
	v_add_f32_e32 v22, v22, v23
	ds_bpermute_b32 v23, v47, v22
	s_waitcnt lgkmcnt(0)
	v_add_f32_e32 v22, v22, v23
	v_fmamk_f32 v22, v22, 0x3a800000, v48
	v_mul_f32_e32 v23, 0x4f800000, v22
	v_cmp_gt_f32_e32 vcc, s12, v22
	s_nop 1
	v_cndmask_b32_e32 v22, v22, v23, vcc
	v_sqrt_f32_e32 v23, v22
	s_nop 0
	v_add_u32_e32 v52, -1, v23
	v_add_u32_e32 v53, 1, v23
	v_fma_f32 v54, -v52, v23, v22
	v_fma_f32 v55, -v53, v23, v22
	v_cmp_ge_f32_e64 s[2:3], 0, v54
	s_nop 1
	v_cndmask_b32_e64 v23, v23, v52, s[2:3]
	v_cmp_lt_f32_e64 s[2:3], 0, v55
	s_nop 1
	v_cndmask_b32_e64 v23, v23, v53, s[2:3]
	v_mul_f32_e32 v52, 0x37800000, v23
	v_cndmask_b32_e32 v23, v23, v52, vcc
	v_cmp_class_f32_e32 vcc, v22, v49
	s_nop 1
	v_cndmask_b32_e32 v22, v23, v22, vcc
	v_div_scale_f32 v23, s[2:3], v22, v22, 1.0
	v_rcp_f32_e32 v52, v23
	v_div_scale_f32 v53, vcc, 1.0, v22, 1.0
	v_fma_f32 v54, -v23, v52, 1.0
	v_fmac_f32_e32 v52, v54, v52
	v_mul_f32_e32 v54, v53, v52
	v_fma_f32 v55, -v23, v54, v53
	v_fmac_f32_e32 v54, v55, v52
	v_fma_f32 v23, -v23, v54, v53
	v_div_fmas_f32 v23, v23, v52, v54
	v_div_fixup_f32 v22, v23, v22, 1.0
	s_and_saveexec_b64 s[2:3], s[0:1]
	s_cbranch_execz .LBB0_3269
	s_ashr_i32 s5, s4, 31
	s_lshl_b64 s[14:15], s[4:5], 2
	s_add_u32 s14, s18, s14
	v_mul_f32_e32 v52, 0x3a800000, v51
	s_addc_u32 s15, s19, s15
	v_mov_b32_e32 v53, v22
	global_store_dwordx2 v50, v[52:53], s[14:15]
